# P0 weight-tile transpose: lanes permuted so the f32 LDS writes are bank-conflict free (4 consecutive lanes take 4 consecutive k rows)
# baseline (speedup 1.0000x reference)
; #define LAS __attribute__((address_space(3)))
; __device__ __forceinline__ f32x4 ldnt(const f32x4* p) { return __builtin_nontemporal_load(p); }
; __device__ __forceinline__ u32x4 ldnt(const u32x4* p) { return __builtin_nontemporal_load(p); }
; __device__ __forceinline__ void prep_tiles(const Params& p, LAS unsigned char* lds, int t_first, int t_end, int stride) {
;     const int tid = threadIdx.x;
;     LAS float* tl = (LAS float*)lds;
;     f32x4 pf[8];
;     if (t_first < t_end) { const float* src; bf16_t* dst; const float* gain; int K, N, k0, n0, drow0; WJOB_DECODE(t_first, src, dst, gain, K, N, k0, n0, drow0);
;         (void)dst; (void)gain; (void)K; (void)drow0;
; #pragma unroll
;         for (int i = 0; i < 8; ++i) { const int e = tid + 512 * i; pf[i] = ldnt((const f32x4*)(src + (size_t)(k0 + (e >> 5)) * N + n0 + (e & 31) * 4)); } }
.LBB0_15:
	s_or_b64 exec, exec, s[62:63]
	v_bfe_u32 v232, v0, 2, 5
	v_lshrrev_b32_e32 v233, 7, v0
	v_lshlrev_b32_e32 v233, 2, v233
	v_and_b32_e32 v234, 3, v0
	v_or_b32_e32 v233, v233, v234
	v_lshl_or_b32 v232, v233, 5, v232
	s_cmpk_lt_i32 s2, 0x2d4
	s_cselect_b64 s[4:5], -1, 0
	s_cmpk_gt_i32 s2, 0x2d3
	s_cbranch_scc1 .LBB0_39
	s_cmpk_lt_i32 s2, 0x80
	s_cbranch_scc1 .LBB0_22
	s_cmpk_gt_u32 s2, 0xbf
	s_cbranch_scc0 .LBB0_23
	s_cmpk_gt_u32 s2, 0x16f
	s_cbranch_scc0 .LBB0_24
	s_cmpk_gt_u32 s2, 0x21f
	s_cbranch_scc0 .LBB0_25
	s_cmpk_gt_u32 s2, 0x2cf
	s_cbranch_scc0 .LBB0_26
	s_load_dwordx16 s[36:51], s[0:1], 0x40
	s_add_i32 s6, s2, 0xfffffd30
	s_mov_b32 s7, 0
	s_lshl_b64 s[6:7], s[6:7], 16
	s_mov_b64 s[8:9], 0
	s_waitcnt lgkmcnt(0)
	s_add_u32 s6, s36, s6
	s_addc_u32 s7, s37, s7
	s_branch .LBB0_27

; __device__ __forceinline__ f32x4 ldnt(const f32x4* p) { return __builtin_nontemporal_load(p); }
; __device__ __forceinline__ u32x4 ldnt(const u32x4* p) { return __builtin_nontemporal_load(p); }
; __device__ __forceinline__ void prep_tiles(const Params& p, LAS unsigned char* lds, int t_first, int t_end, int stride) {
;     ...
;     if (t_first < t_end) { const float* src; bf16_t* dst; const float* gain; int K, N, k0, n0, drow0; WJOB_DECODE(t_first, src, dst, gain, K, N, k0, n0, drow0);
;         (void)dst; (void)gain; (void)K; (void)drow0;
; #pragma unroll
;         for (int i = 0; i < 8; ++i) { const int e = tid + 512 * i; pf[i] = ldnt((const f32x4*)(src + (size_t)(k0 + (e >> 5)) * N + n0 + (e & 31) * 4)); } }
;     for (int t = t_first; t < t_end; t += stride) {
;         f32x4 cf[8];
; #pragma unroll
;         for (int i = 0; i < 8; ++i) cf[i] = pf[i];
;         if (t + stride < t_end) { const float* src; bf16_t* dst; const float* gain; int K, N, k0, n0, drow0; WJOB_DECODE(t + stride, src, dst, gain, K, N, k0, n0, drow0);
;             (void)dst; (void)gain; (void)K; (void)drow0;
; #pragma unroll
;             for (int i = 0; i < 8; ++i) { const int e = tid + 512 * i; pf[i] = ldnt((const f32x4*)(src + (size_t)(k0 + (e >> 5)) * N + n0 + (e & 31) * 4)); } }
; #pragma unroll
;         for (int i = 0; i < 8; ++i) { const int e = tid + 512 * i, kk = e >> 5, n4 = (e & 31) * 4;
;             tl[kk * 129 + n4 + 0] = cf[i][0]; tl[kk * 129 + n4 + 1] = cf[i][1]; tl[kk * 129 + n4 + 2] = cf[i][2]; tl[kk * 129 + n4 + 3] = cf[i][3]; }
.LBB0_38:
	s_lshr_b32 s8, s12, 7
	v_cvt_f32_u32_e32 v1, s8
	s_sub_i32 s15, 0, s8
	s_abs_i32 s14, s13
	s_ashr_i32 s9, s13, 31
	v_rcp_iflag_f32_e32 v1, v1
	v_lshlrev_b32_e32 v2, 4, v232
	v_mov_b32_e32 v3, 0
	v_and_b32_e32 v2, 0x1f0, v2
	v_mul_f32_e32 v1, 0x4f7ffffe, v1
	v_cvt_u32_f32_e32 v1, v1
	v_or_b32_e32 v6, 0x200, v232
	v_lshrrev_b32_e32 v6, 5, v6
	v_readfirstlane_b32 s52, v1
	s_mul_i32 s15, s15, s52
	s_mul_hi_u32 s15, s52, s15
	s_add_i32 s52, s52, s15
	s_mul_hi_u32 s15, s14, s52
	s_mul_i32 s52, s15, s8
	s_sub_i32 s14, s14, s52
	s_add_i32 s53, s15, 1
	s_sub_i32 s52, s14, s8
	s_cmp_ge_u32 s14, s8
	s_cselect_b32 s15, s53, s15
	s_cselect_b32 s14, s52, s14
	s_add_i32 s52, s15, 1
	s_cmp_ge_u32 s14, s8
	s_cselect_b32 s14, s52, s15
	s_xor_b32 s14, s14, s9
	s_sub_i32 s9, s14, s9
	s_lshl_b32 s14, s9, 7
	s_mul_i32 s9, s9, s8
	s_sub_i32 s8, s13, s9
	s_lshl_b32 s8, s8, 7
	s_ashr_i32 s9, s8, 31
	s_lshl_b64 s[8:9], s[8:9], 2
	s_add_u32 s6, s6, s8
	v_lshrrev_b32_e32 v1, 5, v232
	s_addc_u32 s7, s7, s9
	v_or_b32_e32 v1, s14, v1
	v_lshl_add_u64 v[2:3], s[6:7], 0, v[2:3]
	v_mad_u64_u32 v[4:5], s[6:7], v1, s12, 0
	s_ashr_i32 s6, s14, 31
	v_or_b32_e32 v6, s14, v6
	s_mul_i32 s8, s6, s12
	v_mad_u64_u32 v[6:7], s[6:7], v6, s12, 0
	v_add_u32_e32 v5, s8, v5
	v_add_u32_e32 v7, s8, v7
	v_lshl_add_u64 v[4:5], v[4:5], 2, v[2:3]
	v_lshl_add_u64 v[6:7], v[6:7], 2, v[2:3]
	global_load_dwordx4 v[38:41], v[4:5], off nt
	global_load_dwordx4 v[34:37], v[6:7], off nt
	v_or_b32_e32 v6, 0x600, v232
	v_lshrrev_b32_e32 v6, 5, v6
	v_or_b32_e32 v4, 32, v1
	v_or_b32_e32 v6, s14, v6
	v_mad_u64_u32 v[4:5], s[6:7], v4, s12, 0
	v_mad_u64_u32 v[6:7], s[6:7], v6, s12, 0
	v_add_u32_e32 v5, s8, v5
	v_add_u32_e32 v7, s8, v7
	v_lshl_add_u64 v[4:5], v[4:5], 2, v[2:3]
	v_lshl_add_u64 v[6:7], v[6:7], 2, v[2:3]
	global_load_dwordx4 v[46:49], v[4:5], off nt
	global_load_dwordx4 v[42:45], v[6:7], off nt
	v_or_b32_e32 v6, 0xa00, v232
	v_or_b32_e32 v4, 64, v1
	v_lshrrev_b32_e32 v6, 5, v6
	v_mad_u64_u32 v[4:5], s[6:7], v4, s12, 0
	v_or_b32_e32 v6, s14, v6
	v_add_u32_e32 v5, s8, v5
	v_mad_u64_u32 v[6:7], s[6:7], v6, s12, 0
	v_lshl_add_u64 v[4:5], v[4:5], 2, v[2:3]
	v_add_u32_e32 v7, s8, v7
	v_or_b32_e32 v1, 0x60, v1
	v_lshl_add_u64 v[6:7], v[6:7], 2, v[2:3]
	global_load_dwordx4 v[54:57], v[4:5], off nt
	global_load_dwordx4 v[50:53], v[6:7], off nt
	v_mad_u64_u32 v[4:5], s[6:7], v1, s12, 0
	v_or_b32_e32 v1, 0xe00, v232
	v_lshrrev_b32_e32 v1, 5, v1
	v_or_b32_e32 v1, s14, v1
	v_add_u32_e32 v5, s8, v5
	v_mad_u64_u32 v[6:7], s[6:7], v1, s12, 0
	v_lshl_add_u64 v[4:5], v[4:5], 2, v[2:3]
	v_add_u32_e32 v7, s8, v7
	v_lshl_add_u64 v[2:3], v[6:7], 2, v[2:3]
	global_load_dwordx4 v[62:65], v[4:5], off nt
	global_load_dwordx4 v[58:61], v[2:3], off nt
.LBB0_39:
	s_andn2_b64 vcc, exec, s[4:5]
	s_cbranch_vccnz .LBB0_90
	v_or_b32_e32 v5, 0x200, v232
	s_add_u32 s52, s30, 0x2d00000
	v_lshrrev_b32_e32 v72, 5, v5
	v_or_b32_e32 v5, 0x600, v232
	s_addc_u32 s53, s31, 0
	v_lshrrev_b32_e32 v74, 5, v5
	v_or_b32_e32 v5, 0xa00, v232
	s_add_u32 s8, s30, 0x1100000
	v_lshlrev_b32_e32 v1, 2, v232
	v_lshlrev_b32_e32 v4, 3, v0
	v_lshrrev_b32_e32 v76, 5, v5
	v_or_b32_e32 v5, 0xe00, v232
	s_addc_u32 s9, s31, 0
	v_and_b32_e32 v2, 0x7c, v1
	v_and_b32_e32 v68, 24, v4
	v_and_b32_e32 v4, 0x1fc, v0
	v_lshrrev_b32_e32 v69, 5, v232
	v_lshrrev_b32_e32 v78, 5, v5
	s_add_u32 s12, s30, 0x600000
	v_lshl_add_u32 v3, v2, 2, 0
	v_add_u32_e32 v4, 0, v4
	v_mul_u32_u24_e32 v5, 0x204, v68
	v_mul_u32_u24_e32 v6, 0x204, v69
	v_mul_u32_u24_e32 v7, 0x204, v72
	v_mul_u32_u24_e32 v8, 0x204, v74
	v_mul_u32_u24_e32 v9, 0x204, v76
	v_mul_u32_u24_e32 v10, 0x204, v78
	s_addc_u32 s13, s31, 0
	s_add_u32 s14, s30, 0x400000
	v_lshlrev_b32_e32 v70, 2, v2
	v_add_u32_e32 v79, v3, v6
	v_add_u32_e32 v80, v3, v7
	v_add_u32_e32 v81, v3, v8
	v_add_u32_e32 v82, v3, v9
	v_add_u32_e32 v83, v3, v10
	v_add_u32_e32 v84, v4, v5
	s_waitcnt vmcnt(0)
	v_mov_b64_e32 v[26:27], v[58:59]
	v_mov_b64_e32 v[30:31], v[62:63]
	v_mov_b64_e32 v[18:19], v[50:51]
	v_mov_b64_e32 v[22:23], v[54:55]
	v_mov_b64_e32 v[10:11], v[42:43]
	v_mov_b64_e32 v[14:15], v[46:47]
	v_mov_b64_e32 v[2:3], v[34:35]
	v_mov_b64_e32 v[6:7], v[38:39]
	v_mov_b32_e32 v67, 0
	s_mov_b32 s7, 0
	v_lshrrev_b32_e32 v1, 2, v0
	v_or_b32_e32 v73, 32, v69
	v_or_b32_e32 v75, 64, v69
	v_or_b32_e32 v77, 0x60, v69
	s_addc_u32 s15, s31, 0
	v_lshlrev_b32_e32 v66, 1, v68
	s_mov_b32 s55, s2
	v_mov_b64_e32 v[28:29], v[60:61]
	v_mov_b64_e32 v[32:33], v[64:65]
	v_mov_b64_e32 v[20:21], v[52:53]
	v_mov_b64_e32 v[24:25], v[56:57]
	v_mov_b64_e32 v[12:13], v[44:45]
	v_mov_b64_e32 v[16:17], v[48:49]
	v_mov_b64_e32 v[4:5], v[36:37]
	v_mov_b64_e32 v[8:9], v[40:41]
	s_branch .LBB0_42
